# grid barriers: acquire invalidate (buffer_inv sc1) issued with the arrival atomic instead of after the release (CU is quiescent in between); on top of x-loop re-deal and tagged LN exchange
# speedup vs baseline: 1.0185x; 1.0076x over previous
.LBB0_118:
	s_mov_b64 s[6:7], exec
	v_readlane_b32 s0, v254, 4
	s_lshl_b32 s0, s0, 8
	v_readlane_b32 s8, v254, 2
	v_mbcnt_lo_u32_b32 v2, s6, 0
	v_readlane_b32 s9, v254, 3
	s_add_u32 s0, s8, s0
	v_mbcnt_hi_u32_b32 v2, s7, v2
	s_addc_u32 s1, s9, 0
	v_cmp_eq_u32_e32 vcc, 0, v2
	s_and_saveexec_b64 s[8:9], vcc
	s_cbranch_execz .LBB0_120
	s_bcnt1_i32_b64 s6, s[6:7]
	v_mov_b32_e32 v4, 0x1000
	v_mov_b32_e32 v5, s6
	global_atomic_add v4, v4, v5, s[0:1] offset:1024 sc0
	buffer_inv sc1

.LBB0_133:
	s_or_b64 exec, exec, s[8:9]
	s_waitcnt vmcnt(0)
	s_nop 0
	s_waitcnt vmcnt(0)

.LBB0_151:
	s_or_b64 exec, exec, s[6:7]
	s_mov_b64 s[6:7], exec
	v_mbcnt_lo_u32_b32 v1, s6, 0
	v_mbcnt_hi_u32_b32 v1, s7, v1
	v_cmp_eq_u32_e32 vcc, 0, v1
	s_waitcnt vmcnt(0)
	s_nop 0
	s_and_saveexec_b64 s[8:9], vcc
	s_cbranch_execz .LBB0_153
	s_bcnt1_i32_b64 s6, s[6:7]
	v_mov_b32_e32 v1, 0x2000
	v_mov_b32_e32 v2, s6
	global_atomic_add v1, v2, s[0:1] offset:1024

.LBB0_454:
	s_mov_b64 s[6:7], exec
	v_readlane_b32 s0, v254, 4
	s_lshl_b32 s0, s0, 8
	v_readlane_b32 s2, v254, 2
	v_mbcnt_lo_u32_b32 v2, s6, 0
	v_readlane_b32 s3, v254, 3
	s_add_u32 s0, s2, s0
	v_mbcnt_hi_u32_b32 v2, s7, v2
	s_addc_u32 s1, s3, 0
	v_cmp_eq_u32_e32 vcc, 0, v2
	s_and_saveexec_b64 s[8:9], vcc
	s_cbranch_execz .LBB0_456
	s_bcnt1_i32_b64 s2, s[6:7]
	v_mov_b32_e32 v4, 0x1000
	v_mov_b32_e32 v5, s2
	global_atomic_add v4, v4, v5, s[0:1] offset:1024 sc0
	buffer_inv sc1

.LBB0_487:
	s_or_b64 exec, exec, s[2:3]
	s_mov_b64 s[6:7], exec
	v_mbcnt_lo_u32_b32 v1, s6, 0
	v_mbcnt_hi_u32_b32 v1, s7, v1
	v_cmp_eq_u32_e32 vcc, 0, v1
	s_waitcnt vmcnt(0)
	s_nop 0
	s_and_saveexec_b64 s[2:3], vcc
	s_cbranch_execz .LBB0_489
	s_bcnt1_i32_b64 s6, s[6:7]
	v_mov_b32_e32 v1, 0x2000
	v_mov_b32_e32 v2, s6
	global_atomic_add v1, v2, s[0:1] offset:1024
